# split P4 at the round-4 boundary: WGs 0-127 run their 5th in-proj unit while WGs 128-255 start two attention items that depend only on rounds 1-4; attention items come from a per-WG queue (2 early + 3
# speedup vs baseline: 1.0538x; 1.0038x over previous
; template <class Epi, class Sched, bool ALIGN_EPI = false, bool SP2 = false>
; __device__ __forceinline__ void gemm_phase(PG8_LAS unsigned char* lds, const Gemm g, const Sched& S, const Epi& E) {
;     ...
;     const int tid = tid_l, wid = __builtin_amdgcn_readfirstlane(tid >> 6), lane = tid & 63, wr = wid >> 2, wc = wid & 3, fr = lane & 15, fq = lane >> 4;
;     const int K = g.K, nt = K / BK;
;     unsigned voffA[2], voffB[2];
; #pragma unroll
;     for (int i = 0; i < 2; ++i) { int R, C; stage_rc(tid * 16 + i * 8192, R, C); const int Rb = Epi::PERM ? ((R & ~31) + perm32(R & 31)) : R;
;         voffA[i] = (unsigned)(R * K + C) * 2u; voffB[i] = (unsigned)(Rb * K + C) * 2u; }
;     const size_t kstep = (size_t)(BK * 2);
;     const size_t hstep = (size_t)HALF * K * 2;
;     const size_t tstep = 2 * hstep;
;     const unsigned ldsw = (unsigned)wid * 1024u;
;     const int aoff = lds_byte(wr * 64 + fr, fq * 8), boff = lds_byte(wc * 32 + fr, fq * 8);
;     ...
;     Unit cur, nxt; int ui = 0;
;     if (!S.next(0, cur)) return;
;     f32x4 acc[2][2][4][2];
; #pragma unroll
;     for (int a = 0; a < 2; ++a)
; #pragma unroll
;         for (int b = 0; b < 2; ++b)
; #pragma unroll
;             for (int m = 0; m < 4; ++m)
; #pragma unroll
;                 for (int n = 0; n < 2; ++n) acc[a][b][m][n] = (f32x4){0.f, 0.f, 0.f, 0.f};
;     bf16x8 At[4][2], B0[2][2], B1[2][2];
;     const char* cA = (const char*)g.A + (size_t)cur.pm * tstep; const char* cB = (const char*)g.Bt + (size_t)cur.pn * tstep;
;     S.a_ready(cur);
;     if constexpr (SP2) {
;         PG8_STAGE(PG8_SB(0, 0), cB, voffB); PG8_STAGE(PG8_SB(0, 1), cB + hstep, voffB); PG8_STAGE(PG8_SA(0, 0), cA, voffA); PG8_STAGE(PG8_SA(0, 1), cA + hstep, voffA);
;         if (wr == 1) PG8_BAR;
;         PG8_WAIT_V(2); PG8_BAR;
;         PG8_STAGE(PG8_SB(1, 0), cB + kstep, voffB); PG8_STAGE(PG8_SA(1, 0), cA + kstep, voffA); PG8_STAGE(PG8_SB(1, 1), cB + hstep + kstep, voffB);
;         PG8_WAIT_V(6); PG8_BAR;
; __global__ void __launch_bounds__(NTHREADS) fwd_megakernel(Params P) {
;     ...
;     if constexpr ((PH_MASK & 16) != 0) {
;         pg8::Gemm g{(const bf16_t*)(ws + WS_X1B), (const bf16_t*)(ws + WS_BT2), NTOK, N_IN1, DM};
;         pg8::StaticOrder S; S.init(NTOK, N_IN1, G, bid);
;         EpiIn E{1, ws};
;         for (int rep = 0; rep < NREP(4); ++rep) pg8::gemm_phase<EpiIn, pg8::StaticOrder, true, true>(lds, g, S, E);
.LBB0_826:
	s_or_b64 exec, exec, s[0:1]
	s_mov_b32 s100, 0
	v_writelane_b32 v255, s6, 16
	v_writelane_b32 v255, s7, 17
	v_writelane_b32 v255, s34, 18
	v_writelane_b32 v255, s35, 19
	v_writelane_b32 v255, s40, 20
	v_writelane_b32 v255, s41, 21
	v_writelane_b32 v255, s42, 22
	v_writelane_b32 v255, s43, 23
	v_writelane_b32 v255, s70, 24
	v_writelane_b32 v255, s72, 25
	v_writelane_b32 v255, s84, 26
	v_writelane_b32 v255, s85, 27
.Lb3_p4_top:
	s_add_u32 s10, s50, 0xf000000
	s_addc_u32 s11, s51, 0
	v_mov_b32_e32 v11, v234
	s_waitcnt lgkmcnt(0)
	s_barrier
	s_cmpk_lt_i32 s3, 0x480
	s_nop 0
	v_readfirstlane_b32 s1, v11
	s_cbranch_scc0 .LBB0_855
	v_lshlrev_b32_e32 v0, 4, v11
	v_add_u32_e32 v1, 0x2000, v0
	v_ashrrev_i32_e32 v2, 31, v1
	v_lshrrev_b32_e32 v2, 22, v2
	v_add_u32_e32 v2, v1, v2
	v_ashrrev_i32_e32 v8, 10, v2
	v_mul_i32_i24_e32 v2, 0x400, v8
	v_sub_u32_e32 v1, v1, v2
	v_lshrrev_b32_e32 v2, 4, v1
	v_bitop3_b32 v1, v2, v1, 32 bitop3:0x6c
	v_ashrrev_i32_e32 v2, 31, v1
	v_lshrrev_b32_e32 v2, 26, v2
	v_add_u32_e32 v2, v1, v2
	v_lshlrev_b32_e32 v3, 3, v8
	v_ashrrev_i32_e32 v9, 6, v2
	v_and_b32_e32 v3, -16, v3
	v_add_u32_e32 v3, v9, v3
	v_and_b32_e32 v4, 3, v9
	s_mov_b32 s0, 0x1fffe0
	v_lshrrev_b32_e32 v5, 2, v3
	v_lshlrev_b32_e32 v6, 1, v3
	v_and_b32_e32 v2, 0xc0, v2
	v_and_or_b32 v4, v3, s0, v4
	v_and_b32_e32 v5, 4, v5
	v_and_b32_e32 v6, 24, v6
	v_sub_u32_e32 v1, v1, v2
	v_mov_b32_e32 v2, 1
	v_or3_b32 v4, v4, v5, v6
	v_lshlrev_b32_e32 v5, 5, v8
	v_ashrrev_i16_sdwa v1, v2, sext(v1) dst_sel:DWORD dst_unused:UNUSED_PAD src0_sel:DWORD src1_sel:BYTE_0
	v_and_b32_e32 v5, 32, v5
	v_bfe_i32 v10, v1, 0, 16
	v_add_lshl_u32 v1, v5, v10, 1
	v_lshl_add_u32 v132, v4, 11, v1
	v_lshl_add_u32 v134, v3, 11, v1
	v_bfe_i32 v1, v11, 27, 1
	v_lshrrev_b32_e32 v1, 22, v1
	v_add_u32_e32 v1, v0, v1
	v_and_b32_e32 v1, 0xfffffc00, v1
	v_sub_u32_e32 v0, v0, v1
	v_lshrrev_b32_e32 v1, 4, v0
	v_ashrrev_i32_e32 v3, 31, v11
	v_bitop3_b32 v0, v1, v0, 32 bitop3:0x6c
	v_lshrrev_b32_e32 v3, 26, v3
	v_ashrrev_i32_e32 v1, 31, v0
	v_add_u32_e32 v3, v11, v3
	v_lshrrev_b32_e32 v1, 26, v1
	v_ashrrev_i32_e32 v13, 6, v3
	v_add_u32_e32 v1, v0, v1
	v_lshlrev_b32_e32 v3, 3, v13
	v_ashrrev_i32_e32 v12, 6, v1
	v_and_b32_e32 v3, -16, v3
	v_add_u32_e32 v3, v12, v3
	v_and_b32_e32 v4, 3, v12
	v_and_or_b32 v4, v3, s0, v4
	s_lshr_b32 s0, s93, 29
	s_add_i32 s0, s3, s0
	s_ashr_i32 s2, s1, 6
	s_ashr_i32 s4, s0, 3
	s_and_b32 s0, s0, -8
	s_ashr_i32 s12, s1, 8
	s_lshl_b32 s22, s2, 10
	s_sub_i32 s0, s3, s0
	s_cmp_lt_i32 s0, 0
	s_movk_i32 s23, 0x91
	s_cselect_b32 s5, s23, 0x90
	s_mul_i32 s0, s0, s5
	s_add_i32 s0, s0, s4
	s_mul_hi_i32 s4, s0, 0x38e38e39
	s_lshr_b32 s5, s4, 31
	s_ashr_i32 s4, s4, 4
	s_add_i32 s4, s4, s5
	s_lshl_b32 s5, s4, 3
	s_mulk_i32 s4, 0x48
	s_sub_i32 s4, s0, s4
	s_bfe_i32 s0, s4, 0x80000
	s_bfe_u32 s0, s0, 0x3000c
	s_add_i32 s8, s4, s0
	s_bfe_i32 s0, s8, 0x80000
	s_and_b32 s8, s8, 0xf8
	s_sub_i32 s4, s4, s8
	s_sext_i32_i16 s0, s0
	s_sext_i32_i8 s4, s4
	v_lshrrev_b32_e32 v5, 2, v3
	v_lshlrev_b32_e32 v6, 1, v3
	v_and_b32_e32 v1, 0xc0, v1
	s_lshr_b32 s0, s0, 3
	s_add_i32 s4, s5, s4
	v_and_b32_e32 v5, 4, v5
	v_and_b32_e32 v6, 24, v6
	v_sub_u32_e32 v0, v0, v1
	s_ashr_i32 s5, s4, 31
	s_bfe_i64 s[8:9], s[0:1], 0x100000
	v_or3_b32 v4, v4, v5, v6
	v_lshlrev_b32_e32 v5, 5, v13
	v_ashrrev_i16_sdwa v0, v2, sext(v0) dst_sel:DWORD dst_unused:UNUSED_PAD src0_sel:DWORD src1_sel:BYTE_0
	s_lshl_b64 s[14:15], s[4:5], 19
	s_lshl_b64 s[8:9], s[8:9], 19
	v_and_b32_e32 v5, 32, v5
	v_bfe_i32 v14, v0, 0, 16
	s_add_u32 s8, s42, s8
	v_add_lshl_u32 v0, v5, v14, 1
	s_addc_u32 s9, s43, s9
	s_add_i32 s30, s22, 0
	v_lshl_add_u32 v136, v4, 11, v0
	s_add_i32 m0, s30, 0x10000
	v_lshl_add_u32 v138, v3, 11, v0
	global_load_lds_dwordx4 v136, s[8:9]
	s_add_i32 m0, s30, 0x12000
	s_add_u32 s16, s8, 0x40000
	global_load_lds_dwordx4 v132, s[8:9]
	s_addc_u32 s17, s9, 0
	s_add_i32 m0, s30, 0x14000
	v_mov_b32_e32 v141, 0
	global_load_lds_dwordx4 v136, s[16:17]
	s_add_i32 m0, s30, 0x16000
	s_add_u32 s78, s40, s14
	s_addc_u32 s79, s41, s15
	s_add_i32 s31, s30, 0x2000
	global_load_lds_dwordx4 v132, s[16:17]
	s_mov_b32 m0, s30
	s_add_u32 s14, s78, 0x40000
	global_load_lds_dwordx4 v138, s[78:79]
	s_mov_b32 m0, s31
	s_addc_u32 s15, s79, 0
	s_add_i32 s33, s30, 0x4000
	global_load_lds_dwordx4 v134, s[78:79]
	s_mov_b32 m0, s33
	s_add_i32 s53, s30, 0x6000
	global_load_lds_dwordx4 v138, s[14:15]
	s_mov_b32 m0, s53
	v_mov_b32_e32 v137, v141
	global_load_lds_dwordx4 v134, s[14:15]
	v_mov_b32_e32 v133, v141
	v_mov_b32_e32 v139, v141
	v_mov_b32_e32 v135, v141
	s_cmp_eq_u32 s12, 1
	s_mov_b32 s13, 0
	v_lshl_add_u64 v[6:7], s[8:9], 0, v[136:137]
	v_lshl_add_u64 v[2:3], s[8:9], 0, v[132:133]
	v_lshl_add_u64 v[0:1], s[78:79], 0, v[138:139]
	s_cselect_b64 s[14:15], -1, 0
	s_cmp_lg_u32 s12, 1
	v_lshl_add_u64 v[4:5], s[78:79], 0, v[134:135]
	s_cbranch_scc1 .LBB0_829
	s_barrier
; #define PG8_STAGE(bufoff, gbase, voff) do { _Pragma("unroll") for (int _i = 0; _i < 2; ++_i) \
;         __builtin_amdgcn_global_load_lds((const unsigned*)((const char*)(gbase) + (voff)[_i]), (PG8_LAS unsigned*)(lds + (bufoff) + ldsw + _i * 8192), 16, 0, 0); } while (0)
; #define PG8_WAIT_V(n) asm volatile("s_waitcnt vmcnt(" #n ")" ::: "memory")
; #define PG8_BAR __builtin_amdgcn_s_barrier()
;     __host__ __device__ bool next(int i, Unit& u) const {
;         const long L = (long)i * G + c; if (L >= nwg) return false;
;         int wgid = (int)L; { const int q = nwg / NXCD, r = nwg % NXCD, xcd = wgid % NXCD, off = wgid / NXCD; wgid = (xcd < r ? xcd * (q + 1) : r * (q + 1) + (xcd - r) * q) + off; }
;         const int nig = WGM * nN, gid = wgid / nig, fm = gid * WGM, gsz = (nM - fm) < WGM ? (nM - fm) : WGM;
;         u.pm = fm + ((wgid % nig) % gsz); u.pn = (wgid % nig) / gsz; return true;
; template <class Epi, class Sched, bool ALIGN_EPI = false, bool SP2 = false>
; __device__ __forceinline__ void gemm_phase(PG8_LAS unsigned char* lds, const Gemm g, const Sched& S, const Epi& E) {
;     ...
;         PG8_STAGE(PG8_SB(1, 0), cB + kstep, voffB); PG8_STAGE(PG8_SA(1, 0), cA + kstep, voffA); PG8_STAGE(PG8_SB(1, 1), cB + hstep + kstep, voffB);
;         PG8_WAIT_V(6); PG8_BAR;
.LBB0_829:
	s_add_u32 s5, s50, 0x1100500
	s_addc_u32 s44, s51, 0
	s_add_u32 s16, s50, 0x1100400
	s_mov_b64 s[18:19], 0x80
	s_addc_u32 s17, s51, 0
	s_and_b32 s59, s2, 3
	s_add_i32 m0, s30, 0x18000
	v_lshl_add_u64 v[6:7], v[6:7], 0, s[18:19]
	s_lshl_b32 s45, s12, 13
	s_lshl_b32 s46, s59, 12
	s_waitcnt vmcnt(2)
	s_barrier
	global_load_lds_dwordx4 v[6:7], off
	v_lshl_add_u64 v[2:3], v[2:3], 0, s[18:19]
	s_add_i32 m0, s30, 0x1a000
	s_add_i32 s61, s30, 0x8000
	s_add_i32 s69, s30, 0xa000
	global_load_lds_dwordx4 v[2:3], off
	v_lshl_add_u64 v[0:1], v[0:1], 0, s[18:19]
	s_mov_b32 m0, s61
	s_add_u32 s20, s8, 0x40080
	global_load_lds_dwordx4 v[0:1], off
	v_lshl_add_u64 v[0:1], v[4:5], 0, s[18:19]
	s_mov_b32 m0, s69
	s_addc_u32 s21, s9, 0
	global_load_lds_dwordx4 v[0:1], off
	s_add_i32 m0, s30, 0x1c000
	v_lshl_add_u64 v[0:1], s[20:21], 0, v[136:137]
	global_load_lds_dwordx4 v[0:1], off
	v_lshl_add_u64 v[0:1], s[20:21], 0, v[132:133]
	s_add_i32 m0, s30, 0x1e000
	s_or_b32 s86, s59, 0xffffffec
	global_load_lds_dwordx4 v[0:1], off
	v_bfe_u32 v1, v11, 4, 2
	v_and_b32_e32 v0, 15, v11
	v_lshlrev_b32_e32 v140, 4, v1
	v_lshlrev_b32_e32 v2, 2, v11
	s_cmpk_lt_u32 s1, 0x100
	v_lshl_or_b32 v143, s12, 6, v0
	v_lshl_or_b32 v0, v0, 6, v140
	v_and_b32_e32 v2, 32, v2
	s_cselect_b64 s[20:21], -1, 0
	s_cmp_gt_u32 s59, 1
	v_lshl_add_u64 v[144:145], s[6:7], 0, v[140:141]
	v_readlane_b32 s6, v255, 5
	s_sext_i32_i8 s2, s0
	v_lshlrev_b32_e32 v142, 3, v1
	v_bitop3_b32 v3, v0, s45, v2 bitop3:0xde
	v_bitop3_b32 v225, v0, s46, v2 bitop3:0xde
	s_cselect_b64 s[0:1], -1, 0
	v_lshlrev_b32_e32 v0, 6, v1
	v_mov_b32_e32 v1, v141
	v_readlane_b32 s7, v255, 6
	s_add_i32 s12, s59, -2
	s_waitcnt vmcnt(6)
	v_lshl_add_u64 v[148:149], s[10:11], 0, v[140:141]
	v_lshl_add_u64 v[146:147], s[6:7], 0, v[0:1]
	v_cndmask_b32_e64 v0, 0, 1, s[0:1]
	v_and_b32_e32 v1, 1, v13
	v_readfirstlane_b32 s88, v0
	v_lshlrev_b32_e32 v0, 14, v13
	v_and_b32_e32 v0, 0xffff8000, v0
	v_lshl_add_u32 v0, v12, 11, v0
	s_and_b64 s[0:1], s[0:1], exec
	v_lshl_or_b32 v0, v1, 6, v0
	s_mov_b32 s0, 0xe800000
	v_lshl_add_u32 v150, v14, 1, v0
	v_lshlrev_b32_e32 v0, 14, v8
	s_cselect_b32 s0, s0, 0xe000000
	v_and_b32_e32 v0, 0xffff8000, v0
	s_cselect_b32 s45, s35, s44
	s_cselect_b32 s44, s34, s5
	s_add_u32 s46, s50, s0
	v_lshl_add_u32 v0, v9, 11, v0
	v_and_b32_e32 v1, 1, v8
	s_addc_u32 s47, s51, 0
	v_lshl_or_b32 v0, v1, 6, v0
	s_add_i32 s89, 0, 0x10000
	s_add_i32 s90, 0, 0x14000
	s_min_u32 s87, s12, s59
	v_mov_b32_e32 v151, v141
	v_lshl_add_u32 v152, v10, 1, v0
	v_mov_b32_e32 v153, v141
	s_movk_i32 vcc_lo, 0x480
	s_movk_i32 vcc_hi, 0x47f
	s_cmp_eq_u32 s100, 0
	s_cselect_b32 vcc_lo, 0x400, vcc_lo
	s_cselect_b32 vcc_hi, 0x3ff, vcc_hi
	v_mov_b32_e32 v154, vcc_lo
	v_mov_b32_e32 v155, 0
	v_mov_b32_e32 v156, vcc_hi
	v_mov_b32_e32 v157, 0
	v_add_u32_e32 v226, s89, v225
	v_add_u32_e32 v227, s90, v225
	v_add_u32_e32 v228, 0, v3
	v_mbcnt_hi_u32_b32 v229, -1, v224
	s_mov_b32 s52, 0x3a800000
	s_mov_b32 s58, 0x358637bd
	s_mov_b32 s91, 0x800000
	s_mov_b32 s60, 0x45800000
	s_mov_b64 s[62:63], 0x4800
	s_mov_b64 s[64:65], 0x5000
	s_movk_i32 s94, 0x5000
	s_mov_b64 s[66:67], 0x5800
	s_mov_b32 s68, 0x3c800000
	s_mov_b32 s95, 0
	s_barrier
	s_branch .LBB0_832

; __device__ __forceinline__ void xcd_barrier(const XcdBarrier& b) {
;     asm volatile("s_waitcnt vmcnt(0)" ::: "memory");
;     __syncthreads();
;     if (threadIdx.x == 0) {
;         unsigned* bar = b.bar;
;         __builtin_amdgcn_s_waitcnt(0);
;         unsigned nloc = b.st[0], nx = b.st[1];
;         if (nloc == 0u) { xcd_barrier_complete(bar, b.x, nloc, nx); b.st[0] = nloc; b.st[1] = nx; }
; __global__ void __launch_bounds__(NTHREADS) fwd_megakernel(Params P) {
;     ...
;     xcd_barrier(xbar);
;     if constexpr ((PH_MASK & 32) != 0) {
.LBB0_855:
	v_writelane_b32 v255, s10, 32
	v_writelane_b32 v255, s11, 33
	v_writelane_b32 v255, s18, 34
	v_writelane_b32 v255, s19, 35
	v_writelane_b32 v255, s20, 36
	v_writelane_b32 v255, s21, 37
	v_writelane_b32 v255, s34, 38
	v_writelane_b32 v255, s35, 39
	s_waitcnt vmcnt(0)
	s_barrier
	s_mov_b64 s[0:1], exec
	v_readlane_b32 s4, v255, 3
	v_readlane_b32 s5, v255, 4
	s_and_b64 s[4:5], s[0:1], s[4:5]
	s_xor_b64 s[0:1], s[4:5], s[0:1]
	s_mov_b64 exec, s[4:5]
	s_cbranch_execz .LBB0_908
	s_add_i32 s2, 0, 0x267f0
	v_mov_b32_e32 v0, s2
	s_waitcnt vmcnt(0) expcnt(0) lgkmcnt(0)
	ds_read_b32 v2, v0
	s_add_i32 s2, 0, 0x267f4
	v_mov_b32_e32 v0, s2
	ds_read_b32 v0, v0
	s_waitcnt lgkmcnt(1)
	v_cmp_ne_u32_e32 vcc, 0, v2
	s_cbranch_vccnz .LBB0_871
	s_add_u32 s4, s50, 0x1180200
	s_addc_u32 s5, s51, 0
	s_add_u32 s6, s50, 0x1180400
	s_addc_u32 s7, s51, 0
	s_add_u32 s8, s50, 0x1180500
	s_addc_u32 s9, s51, 0
	s_add_u32 s12, s50, 0x1180600
	s_addc_u32 s13, s51, 0
	s_add_u32 s14, s50, 0x1180700
	s_addc_u32 s15, s51, 0
	s_add_u32 s16, s50, 0x1180800
	s_addc_u32 s17, s51, 0
	s_add_u32 s18, s50, 0x1180900
	s_addc_u32 s19, s51, 0
	s_add_u32 s20, s50, 0x1180a00
	s_addc_u32 s21, s51, 0
	s_add_u32 s34, s50, 0x1180b00
	s_addc_u32 s35, s51, 0
	s_add_u32 s40, s50, 0x1180c00
	s_addc_u32 s41, s51, 0
	s_add_u32 s42, s50, 0x1180d00
	s_addc_u32 s43, s51, 0
	s_add_u32 s44, s50, 0x1180e00
	s_addc_u32 s45, s51, 0
	s_add_u32 s46, s50, 0x1180f00
	s_addc_u32 s47, s51, 0
	s_add_u32 s52, s50, 0x1181000
	s_addc_u32 s53, s51, 0
	s_add_u32 s58, s50, 0x1181100
	s_addc_u32 s59, s51, 0
	s_add_u32 s60, s50, 0x1181200
	v_readlane_b32 s2, v255, 0
	s_addc_u32 s61, s51, 0
	s_mul_i32 s2, s25, s2
	s_add_u32 s62, s50, 0x1181300
	s_mul_i32 s2, s2, s24
	s_addc_u32 s63, s51, 0
	s_mov_b32 s22, 1
	v_mov_b32_e32 v16, 0
	s_branch .LBB0_859

; #define PHASE_IDS() int tid_l = threadIdx.x; asm volatile("" : "+v"(tid_l)); const int tid = tid_l, lane = tid & 63, wid = __builtin_amdgcn_readfirstlane(tid >> 6); (void)lane; (void)wid
; #define P5_DECODE(it_, b_, hq_, ch_) do { const int j_ = (it_) >> 8, c_ = (it_) & 255, idx_ = j_ * 32 + (c_ >> 3)  , bkv_ = (c_ & 7) * 2 + (idx_ >> 6), rem_ = idx_ & 63; \
;         (b_) = bkv_ >> 1; (hq_) = (bkv_ & 1) * 8 + 2 * (rem_ >> 4); (ch_) = rem_ & 15; } while (0)
; DI void c_item_first_loads(unsigned char* ws, int b, int hq, int chunk, int wid, int lane, bf16x8 (&qfa)[4], bf16x8 (&qfb)[4], TileRegs& tr) {
;     const int r = lane & 31, h = lane >> 5, kvh = hq >> 3;
;     const bf16_t* Qa = (const bf16_t*)(ws + WS_QC) + ((size_t)b * 16 + hq) * SEQ * 64;
;     const bf16_t* K = (const bf16_t*)(ws + WS_KC) + ((size_t)b * 2 + kvh) * SEQ * 64;
;     const bf16_t* V = (const bf16_t*)(ws + WS_VTC) + ((size_t)b * 2 + kvh) * SEQ * 64;
;     const int t0 = chunk * 256 + wid * 32, qpos = t0 + r;
;     const bf16x8* qp = (const bf16x8*)(Qa + (size_t)qpos * 64);
; #pragma unroll
;     for (int ks = 0; ks < 4; ++ks) { qfa[ks] = qp[2 * ks + h]; qfb[ks] = qp[SEQ * 8 + 2 * ks + h]; }
;     const int T = (t0 >= 128) ? 0 : (128 - t0) / 32;
;     tile_gload(tr, K, V, t0 - 128 + 32 * T, 1, lane);
; }
; __global__ void __launch_bounds__(NTHREADS) fwd_megakernel(Params P) {
;     ...
;     if constexpr ((PH_MASK & 32) != 0) {
;         PHASE_IDS();
;     ...
;         for (int rep = 0; rep < NREP(5); ++rep) {
;             bf16x8 qfa[4], qfb[4]; TileRegs tr;
;             if (bid < 1024) { int b0, hq0, ch0; P5_DECODE(bid, b0, hq0, ch0); c_item_first_loads(ws, b0, hq0, ch0, wid, lane, qfa, qfb, tr); }
;             for (int it = bid; it < 1024; it += G) {
;                 int b1, hq1, ch1; P5_DECODE(it, b1, hq1, ch1);
;                 const bool hasn = (it + G) < 1024;
;                 int b2 = b1, hq2 = hq1, ch2 = ch1; if (hasn) P5_DECODE(it + G, b2, hq2, ch2);
;                 attn_c_item(ws, lds + wid * TBUF, b1, hq1, ch1, wid, lane, qfa, qfb, tr, hasn, b2, hq2, ch2);
.Lb3_disp:
	s_cmp_eq_u32 s100, 0
	s_cbranch_scc0 .Lb3_not0
	s_cmpk_lt_u32 s3, 0x80
	s_cbranch_scc0 .Lb3_idle
	s_mov_b32 s100, 1
	v_readlane_b32 s6, v255, 16
	v_readlane_b32 s7, v255, 17
	v_readlane_b32 s34, v255, 18
	v_readlane_b32 s35, v255, 19
	v_readlane_b32 s40, v255, 20
	v_readlane_b32 s41, v255, 21
	v_readlane_b32 s42, v255, 22
	v_readlane_b32 s43, v255, 23
	v_readlane_b32 s70, v255, 24
	v_readlane_b32 s72, v255, 25
	v_readlane_b32 s84, v255, 26
	v_readlane_b32 s85, v255, 27
	s_addk_i32 s3, 0x400
	s_branch .Lb3_p4_top
.Lb3_idle:
	s_mov_b32 s100, 2
	s_mov_b32 s101, s3
	s_and_b32 s0, s101, 7
	s_lshr_b32 s1, s101, 3
	s_and_b32 s1, s1, 15
	s_and_b32 s4, s1, 8
	s_add_i32 s4, s4, s1
	s_lshl_b32 s4, s4, 3
	s_or_b32 s3, s4, s0
	s_add_i32 s99, s3, 0x100
	s_or_b32 s99, s99, 0x200000
	s_branch .Lb3_go
.Lb3_not0:
	s_cmp_eq_u32 s100, 1
	s_cbranch_scc0 .Lb3_late
	s_addk_i32 s3, 0xfc00
	s_mov_b32 s101, s3
.Lb3_late:
	s_mov_b32 s100, 4
	s_and_b32 s0, s101, 7
	s_lshr_b32 s1, s101, 3
	s_lshr_b32 s2, s1, 4
	s_and_b32 s1, s1, 15
	s_and_b32 s4, s1, 8
	s_add_i32 s4, s4, s1
	s_add_i32 s3, s4, 8
	s_lshl_b32 s3, s3, 3
	s_or_b32 s3, s3, s0
	s_lshl_b32 s1, s2, 9
	s_add_i32 s3, s3, s1
	s_lshl_b32 s4, s4, 3
	s_or_b32 s4, s4, s0
	s_lshl_b32 s1, s2, 8
	s_add_i32 s4, s4, s1
	s_addk_i32 s4, 0x200
	s_lshl_b32 s4, s4, 11
	s_add_i32 s99, s3, 0x100
	s_or_b32 s99, s99, s4
.Lb3_go:
	s_cmpk_lt_i32 s3, 0x400
	v_readfirstlane_b32 s0, v0
	s_cbranch_scc0 .LBB0_928
	s_ashr_i32 s14, s0, 6
	s_mul_i32 s0, s14, 0x2400
	s_add_i32 s2, s0, 0
	s_add_u32 s22, s50, 0xe800000
	s_addc_u32 s23, s51, 0
	s_lshl_b32 s30, s14, 5
	s_add_u32 s6, s50, 0x1100600
	s_addc_u32 s7, s51, 0
	s_add_u32 s8, s50, 0x1100648
	s_addc_u32 s9, s51, 0
	s_lshl_b32 s0, s3, 1
	s_and_b32 s0, s0, 14
	s_ashr_i32 s4, s3, 9
	s_add_i32 s0, s0, s4
	s_ashr_i32 s0, s0, 1
	s_lshl_b32 s4, s4, 3
	s_ashr_i32 s1, s0, 31
	s_and_b32 s15, s4, 8
	s_lshl_b64 s[4:5], s[0:1], 20
	s_lshl_b32 s12, s15, 16
	s_or_b32 s4, s4, s12
	s_add_u32 s12, s22, s4
	s_addc_u32 s13, s23, s5
	s_and_b32 s16, s3, 0x78
	s_add_i32 s16, s14, s16
	s_lshl_b32 s16, s16, 5
	s_max_i32 s17, s16, 0x80
	s_add_i32 s17, s17, 0x1ffff80
	s_add_u32 s4, s38, s4
	s_addc_u32 s5, s39, s5
	s_lshl_b64 s[0:1], s[0:1], 23
	v_bfe_u32 v1, v0, 3, 3
	v_lshlrev_b32_e32 v3, 4, v0
	s_add_u32 s0, s36, s0
	v_and_b32_e32 v236, 0x70, v3
	v_or_b32_e32 v3, s17, v1
	s_addc_u32 s1, s37, s1
	s_lshr_b32 s17, s3, 6
	s_and_b32 s17, s17, 6
	v_and_b32_e32 v235, 31, v0
	s_or_b32 s15, s15, s17
	s_lshl_b32 s15, s15, 19
	v_or_b32_e32 v4, s16, v235
	s_add_u32 s0, s0, s15
	v_ashrrev_i32_e32 v5, 31, v4
	v_bfe_u32 v2, v0, 5, 1
	v_mov_b32_e32 v195, 0
	s_addc_u32 s1, s1, 0
	v_lshlrev_b64 v[4:5], 7, v[4:5]
	v_lshlrev_b32_e32 v192, 4, v2
	v_lshl_add_u64 v[4:5], s[0:1], 0, v[4:5]
	v_mov_b32_e32 v193, v195
	v_lshl_add_u64 v[4:5], v[4:5], 0, v[192:193]
	s_mov_b32 s31, 0x80000
	v_lshl_or_b32 v3, v3, 7, v236
	v_add_co_u32_e32 v6, vcc, s31, v4
	v_or_b32_e32 v8, 0xc00, v3
	v_or_b32_e32 v9, 0x800, v3
	v_or_b32_e32 v10, 0x400, v3
	v_addc_co_u32_e32 v7, vcc, 0, v5, vcc
	global_load_dwordx4 v[152:155], v[4:5], off
	global_load_dwordx4 v[148:151], v[4:5], off offset:32
	global_load_dwordx4 v[172:175], v[6:7], off
	global_load_dwordx4 v[164:167], v[6:7], off offset:32
	global_load_dwordx4 v[156:159], v[4:5], off offset:64
	global_load_dwordx4 v[144:147], v[4:5], off offset:96
	global_load_dwordx4 v[168:171], v[6:7], off offset:64
	global_load_dwordx4 v[160:163], v[6:7], off offset:96
	global_load_dwordx4 v[112:115], v3, s[4:5]
	global_load_dwordx4 v[116:119], v3, s[12:13]
	global_load_dwordx4 v[120:123], v10, s[4:5]
	global_load_dwordx4 v[124:127], v10, s[12:13]
	global_load_dwordx4 v[128:131], v9, s[4:5]
	global_load_dwordx4 v[132:135], v9, s[12:13]
	global_load_dwordx4 v[136:139], v8, s[4:5]
	global_load_dwordx4 v[140:143], v8, s[12:13]
	s_movk_i32 s0, 0x90
	v_mov_b32_e32 v4, s2
	v_lshlrev_b32_e32 v6, 1, v0
	v_lshlrev_b32_e32 v3, 2, v2
	v_mad_u32_u24 v237, v235, s0, v4
	v_lshrrev_b32_e32 v4, 2, v0
	v_and_b32_e32 v6, 32, v6
	v_lshlrev_b32_e32 v0, 3, v0
	v_mad_u32_u24 v193, v1, s0, v236
	v_and_or_b32 v4, v4, 3, v3
	v_add_u32_e32 v6, s2, v6
	v_and_b32_e32 v0, 24, v0
	v_or_b32_e32 v238, 0x1ffff80, v1
	s_lshl_b32 s4, s14, 12
	v_lshlrev_b32_e32 v1, 7, v1
	v_mul_u32_u24_e32 v5, 0x90, v4
	v_mad_u32_u24 v4, v4, s0, v6
	v_add_u32_e32 v6, v6, v0
	v_lshlrev_b32_e32 v194, 3, v2
	v_or3_b32 v1, s4, v1, v236
	s_movk_i32 s33, 0x80
	v_lshl_add_u64 v[196:197], s[10:11], 0, v[194:195]
	v_sub_u32_e32 v239, v235, v3
	v_cmp_ne_u32_e64 s[0:1], 31, v235
	v_lshl_add_u64 v[198:199], s[26:27], 0, v[194:195]
	v_or_b32_e32 v240, 0x80, v235
	v_sub_u32_e32 v241, 0, v3
	v_add_u32_e32 v242, 0xffffd000, v1
	s_movk_i32 s34, 0x7f
	s_movk_i32 s35, 0xff7f
	v_lshlrev_b32_e32 v194, 4, v2
	s_mov_b32 s40, 0x3fb8aa3b
	v_mbcnt_hi_u32_b32 v243, -1, v224
	s_mov_b32 s41, 0xefa18f08
	v_mov_b32_e32 v244, 0xf149f2ca
	v_add_u32_e32 v245, v4, v0
	v_add_u32_e32 v246, v6, v5
	s_mov_b32 s4, s3
	s_branch .LBB0_911

; #define P5_DECODE(it_, b_, hq_, ch_) do { const int j_ = (it_) >> 8, c_ = (it_) & 255, idx_ = j_ * 32 + (c_ >> 3)  , bkv_ = (c_ & 7) * 2 + (idx_ >> 6), rem_ = idx_ & 63; \
;         (b_) = bkv_ >> 1; (hq_) = (bkv_ & 1) * 8 + 2 * (rem_ >> 4); (ch_) = rem_ & 15; } while (0)
; __global__ void __launch_bounds__(NTHREADS) fwd_megakernel(Params P) {
;     ...
;             for (int it = bid; it < 1024; it += G) {
;                 int b1, hq1, ch1; P5_DECODE(it, b1, hq1, ch1);
;                 const bool hasn = (it + G) < 1024;
;                 int b2 = b1, hq2 = hq1, ch2 = ch1; if (hasn) P5_DECODE(it + G, b2, hq2, ch2);
.LBB0_911:
	s_lshl_b32 s5, s4, 1
	s_and_b32 s5, s5, 14
	s_ashr_i32 s10, s4, 9
	s_add_i32 s5, s5, s10
	s_ashr_i32 s16, s5, 1
	s_lshl_b32 s5, s10, 3
	s_lshr_b32 s10, s4, 6
	s_and_b32 s5, s5, 8
	s_and_b32 s10, s10, 6
	s_or_b32 s43, s5, s10
	s_bfe_u32 s13, s4, 0x40003
	s_and_b32 s42, s99, 0x7ff
	s_lshr_b32 s99, s99, 11
	s_or_b32 s99, s99, 0x200000
	s_cmpk_lt_i32 s42, 0x400
	s_cselect_b64 s[14:15], -1, 0
	s_cmpk_gt_i32 s42, 0x3ff
	s_cselect_b64 s[10:11], -1, 0
	s_and_b64 vcc, exec, s[10:11]
	s_mov_b32 s45, s13
	s_mov_b32 s44, s43
	s_mov_b32 s12, s16
	s_cbranch_vccnz .LBB0_913
	s_lshl_b32 s12, s42, 1
	s_and_b32 s12, s12, 14
	s_ashr_i32 s17, s42, 9
	s_add_i32 s12, s12, s17
	s_lshl_b32 s17, s17, 3
	s_lshr_b32 s18, s42, 6
	s_and_b32 s17, s17, 8
	s_and_b32 s18, s18, 6
	s_ashr_i32 s12, s12, 1
	s_or_b32 s44, s17, s18
	s_bfe_u32 s45, s42, 0x40003

; #define P5_DECODE(it_, b_, hq_, ch_) do { const int j_ = (it_) >> 8, c_ = (it_) & 255, idx_ = j_ * 32 + (c_ >> 3)  , bkv_ = (c_ & 7) * 2 + (idx_ >> 6), rem_ = idx_ & 63; \
;         (b_) = bkv_ >> 1; (hq_) = (bkv_ & 1) * 8 + 2 * (rem_ >> 4); (ch_) = rem_ & 15; } while (0)
; __global__ void __launch_bounds__(NTHREADS) fwd_megakernel(Params P) {
;     ...
;             for (int it = bid; it < 1024; it += G) {
;                 int b1, hq1, ch1; P5_DECODE(it, b1, hq1, ch1);
;                 const bool hasn = (it + G) < 1024;
;                 int b2 = b1, hq2 = hq1, ch2 = ch1; if (hasn) P5_DECODE(it + G, b2, hq2, ch2);
;                 attn_c_item(ws, lds + wid * TBUF, b1, hq1, ch1, wid, lane, qfa, qfb, tr, hasn, b2, hq2, ch2);
;             }
;         }
;     ...
;     }
;     xcd_barrier(xbar);
.LBB0_928:
	v_mbcnt_lo_u32_b32 v224, -1, 0
	s_mov_b32 s3, s101
	s_cmp_eq_u32 s100, 2
	s_cbranch_scc0 .Lb3_done
	s_waitcnt vmcnt(0)
	s_mov_b32 s100, 3
	v_readlane_b32 s10, v255, 32
	v_readlane_b32 s11, v255, 33
	v_readlane_b32 s18, v255, 34
	v_readlane_b32 s19, v255, 35
	v_readlane_b32 s20, v255, 36
	v_readlane_b32 s21, v255, 37
	v_readlane_b32 s34, v255, 38
	v_readlane_b32 s35, v255, 39
	s_branch .LBB0_855

; __global__ void __launch_bounds__(NTHREADS) fwd_megakernel(Params P) {
	.amdhsa_kernel _Z14fwd_megakernel6Params
		.amdhsa_group_segment_fixed_size 0
		.amdhsa_private_segment_fixed_size 0
		.amdhsa_kernarg_size 384
		.amdhsa_user_sgpr_count 2
		.amdhsa_user_sgpr_dispatch_ptr 0
		.amdhsa_user_sgpr_queue_ptr 0
		.amdhsa_user_sgpr_kernarg_segment_ptr 1
		.amdhsa_user_sgpr_dispatch_id 0
		.amdhsa_user_sgpr_kernarg_preload_length 0
		.amdhsa_user_sgpr_kernarg_preload_offset 0
		.amdhsa_user_sgpr_private_segment_size 0
		.amdhsa_uses_dynamic_stack 0
		.amdhsa_enable_private_segment 0
		.amdhsa_system_sgpr_workgroup_id_x 1
		.amdhsa_system_sgpr_workgroup_id_y 0
		.amdhsa_system_sgpr_workgroup_id_z 0
		.amdhsa_system_sgpr_workgroup_info 0
		.amdhsa_system_vgpr_workitem_id 2
		.amdhsa_next_free_vgpr 256
		.amdhsa_next_free_sgpr 102
		.amdhsa_accum_offset 256
		.amdhsa_reserve_vcc 1
		.amdhsa_float_round_mode_32 0
		.amdhsa_float_round_mode_16_64 0
		.amdhsa_float_denorm_mode_32 3
		.amdhsa_float_denorm_mode_16_64 3
		.amdhsa_dx10_clamp 1
		.amdhsa_ieee_mode 1
		.amdhsa_fp16_overflow 0
		.amdhsa_tg_split 0
		.amdhsa_exception_fp_ieee_invalid_op 0
		.amdhsa_exception_fp_denorm_src 0
		.amdhsa_exception_fp_ieee_div_zero 0
		.amdhsa_exception_fp_ieee_overflow 0
		.amdhsa_exception_fp_ieee_underflow 0
		.amdhsa_exception_fp_ieee_inexact 0
		.amdhsa_exception_int_div_zero 0
	.end_amdhsa_kernel

; __global__ void __launch_bounds__(NTHREADS) fwd_megakernel(Params P) {
amdhsa.kernels:
  - .agpr_count:     0
    .args:
      - .offset:         0
        .size:           128
        .value_kind:     by_value
      - .offset:         128
        .size:           4
        .value_kind:     hidden_block_count_x
      - .offset:         132
        .size:           4
        .value_kind:     hidden_block_count_y
      - .offset:         136
        .size:           4
        .value_kind:     hidden_block_count_z
      - .offset:         140
        .size:           2
        .value_kind:     hidden_group_size_x
      - .offset:         142
        .size:           2
        .value_kind:     hidden_group_size_y
      - .offset:         144
        .size:           2
        .value_kind:     hidden_group_size_z
      - .offset:         146
        .size:           2
        .value_kind:     hidden_remainder_x
      - .offset:         148
        .size:           2
        .value_kind:     hidden_remainder_y
      - .offset:         150
        .size:           2
        .value_kind:     hidden_remainder_z
      - .offset:         168
        .size:           8
        .value_kind:     hidden_global_offset_x
      - .offset:         176
        .size:           8
        .value_kind:     hidden_global_offset_y
      - .offset:         184
        .size:           8
        .value_kind:     hidden_global_offset_z
      - .offset:         192
        .size:           2
        .value_kind:     hidden_grid_dims
      - .offset:         216
        .size:           8
        .value_kind:     hidden_multigrid_sync_arg
      - .offset:         248
        .size:           4
        .value_kind:     hidden_dynamic_lds_size
    .group_segment_fixed_size: 0
    .kernarg_segment_align: 8
    .kernarg_segment_size: 384
    .language:       OpenCL C
    .language_version:
      - 2
      - 0
    .max_flat_workgroup_size: 512
    .name:           _Z14fwd_megakernel6Params
    .private_segment_fixed_size: 0
    .sgpr_count:     108
    .sgpr_spill_count: 16
    .symbol:         _Z14fwd_megakernel6Params.kd
    .uniform_work_group_size: 1
    .uses_dynamic_stack: false
    .vgpr_count:     256
    .vgpr_spill_count: 0
    .wavefront_size: 64
